# w_in conversion loop (in-phase tail): four row loads of an item issued together (one round trip per item instead of two)
# speedup vs baseline: 1.0015x; 1.0015x over previous
.LBB0_447:
	s_or_saveexec_b64 s[26:27], s[26:27]
	s_lshl_b32 s55, s55, 10
	s_sub_i32 s56, 0, s55
	v_mov_b32_e32 v4, 0
	v_mov_b32_e32 v5, 0
	v_mov_b32_e32 v6, 0
	v_mov_b32_e32 v7, 0
	v_mov_b32_e32 v0, 0
	v_mov_b32_e32 v1, 0
	v_mov_b32_e32 v2, 0
	v_mov_b32_e32 v3, 0
	s_xor_b64 exec, exec, s[26:27]
	s_cbranch_execz .LBB0_439
	s_ashr_i32 s55, s54, 31
	v_lshl_add_u64 v[20:21], s[54:55], 2, v[8:9]
	s_add_i32 s54, s56, s23
	v_add_u32_e32 v22, s54, v19
	v_add_u32_e32 v32, 0xffffc000, v22
	s_mov_b32 s36, 0x8440
	v_mad_i64_i32 v[32:33], s[54:55], v32, s36, v[20:21]
	global_load_dwordx4 v[32:35], v[32:33], off nt
	v_add_u32_e32 v36, 0xffffc010, v22
	v_mad_i64_i32 v[36:37], s[54:55], v36, s36, v[20:21]
	global_load_dwordx4 v[36:39], v[36:37], off nt
	v_add_u32_e32 v0, 0xffffc020, v22
	v_add_u32_e32 v4, 0xffffc030, v22
	v_mad_i64_i32 v[0:1], s[54:55], v0, s36, v[20:21]
	v_mad_i64_i32 v[4:5], s[54:55], v4, s36, v[20:21]
	global_load_dwordx4 v[0:3], v[0:1], off nt
	s_nop 0
	global_load_dwordx4 v[4:7], v[4:5], off nt
	s_waitcnt vmcnt(2)
	ds_write2_b32 v14, v32, v33 offset1:1
	ds_write2_b32 v14, v34, v35 offset0:2 offset1:3
	ds_write2_b32 v15, v36, v37 offset1:1
	ds_write2_b32 v15, v38, v39 offset0:2 offset1:3
	s_branch .LBB0_439
